# v51: v49 + XCD leader issues its own L1 acquire after the atomic that releases its XCD's waiters (8 barrier sites)
# baseline (speedup 1.0000x reference)
.LBB0_268:
	s_or_b64 exec, exec, s[4:5]
	s_mov_b64 s[4:5], exec
	v_mbcnt_lo_u32_b32 v0, s4, 0
	v_mbcnt_hi_u32_b32 v0, s5, v0
	v_cmp_eq_u32_e32 vcc, 0, v0
	s_waitcnt vmcnt(0)
	s_and_saveexec_b64 s[6:7], vcc
	s_cbranch_execz .LBB0_270
	s_bcnt1_i32_b64 s4, s[4:5]
	v_mov_b32_e32 v0, s4
	v_readlane_b32 s4, v254, 33
	v_readlane_b32 s5, v254, 34
	s_nop 4
	global_atomic_add v201, v0, s[4:5]
.LBB0_270:
	s_or_b64 exec, exec, s[6:7]
	buffer_inv sc1
	s_waitcnt vmcnt(0)

.Lxl_5:
	s_mov_b64 s[4:5], exec
	v_mbcnt_lo_u32_b32 v0, s4, 0
	v_mbcnt_hi_u32_b32 v0, s5, v0
	v_cmp_eq_u32_e32 vcc, 0, v0
	s_waitcnt vmcnt(0)
	s_and_saveexec_b64 s[6:7], vcc
	s_cbranch_execz .LBB0_702
	s_bcnt1_i32_b64 s4, s[4:5]
	v_mov_b32_e32 v0, s4
	v_readlane_b32 s4, v254, 33
	v_readlane_b32 s5, v254, 34
	s_nop 4
	global_atomic_add v201, v0, s[4:5]
